# GEMM loops: LDS-DMA stages use SGPR base + 32-bit VGPR offset (16 v_lshl_add_u64 per trip -> scalar adds), dup lgkm waits removed, pointer increments moved to phase-4, last-trip select only on last tr
# speedup vs baseline: 1.0160x; 1.0060x over previous
; DI unsigned pk2(float a, float b) { typedef _Float16 h2 __attribute__((ext_vector_type(2))); h2 v; v[0] = (f16)a; v[1] = (f16)b; return __builtin_bit_cast(unsigned, v); }
;   DI void operator()(const f32x4 (&acc)[2][2][4][2], const GUnit& u, int wr, int wc, int fr, int fq) const {
;     ...
; #pragma unroll
;     for (int ai = 0; ai < 2; ++ai)
; #pragma unroll
;       for (int m = 0; m < 4; ++m) {
;         f16* zp = base + (size_t)(row0 + ai * 128 + m * 16) * ld + u.pn * 256 + 32 * wc + 8 * fq;
; #pragma unroll
;         for (int bj = 0; bj < 2; ++bj) {
;           f32x4 v0 = acc[ai][bj][m][0], v1 = acc[ai][bj][m][1];
;           if (seg == 5) { v0 *= QSCALE; v1 *= QSCALE; }
;           u32x4_ w; w.x = pk2(v0[0], v0[1]); w.y = pk2(v0[2], v0[3]); w.z = pk2(v1[0], v1[1]); w.w = pk2(v1[2], v1[3]);
;           __builtin_nontemporal_store(w, (u32x4_*)(zp + bj * 128));
;         }
.Lpl_skip1:
	s_waitcnt lgkmcnt(8)
	s_barrier
	s_waitcnt lgkmcnt(0)
	v_mfma_f32_16x16x32_f16 v[58:61], v[130:133], v[170:173], v[58:61]
	v_mfma_f32_16x16x32_f16 v[62:65], v[138:141], v[170:173], v[62:65]
	v_mfma_f32_16x16x32_f16 v[50:53], v[130:133], v[178:181], v[50:53]
	v_mfma_f32_16x16x32_f16 v[54:57], v[138:141], v[178:181], v[54:57]
	v_mfma_f32_16x16x32_f16 v[42:45], v[130:133], v[186:189], v[42:45]
	v_mfma_f32_16x16x32_f16 v[46:49], v[138:141], v[186:189], v[46:49]
	v_mfma_f32_16x16x32_f16 v[26:29], v[130:133], v[194:197], v[26:29]
	v_mfma_f32_16x16x32_f16 v[30:33], v[138:141], v[194:197], v[30:33]
	v_mfma_f32_16x16x32_f16 v[58:61], v[134:137], v[174:177], v[58:61]
	v_mfma_f32_16x16x32_f16 v[62:65], v[142:145], v[174:177], v[62:65]
	v_mfma_f32_16x16x32_f16 v[50:53], v[134:137], v[182:185], v[50:53]
	v_mfma_f32_16x16x32_f16 v[54:57], v[142:145], v[182:185], v[54:57]
	v_mfma_f32_16x16x32_f16 v[42:45], v[134:137], v[190:193], v[42:45]
	v_mfma_f32_16x16x32_f16 v[46:49], v[142:145], v[190:193], v[46:49]
	v_mfma_f32_16x16x32_f16 v[26:29], v[134:137], v[198:201], v[26:29]
	v_mfma_f32_16x16x32_f16 v[30:33], v[142:145], v[198:201], v[30:33]
	s_barrier
	s_mov_b32 m0, s54
	ds_read_b128 v[202:205], v254 offset:16384
	ds_read_b128 v[206:209], v254 offset:17408
	s_add_u32 s96, s46, s30
	ds_read_b128 v[210:213], v254 offset:18432
	ds_read_b128 v[214:217], v254 offset:19456
	global_load_lds_dwordx4 v148, s[46:47]
	s_addc_u32 s97, s47, s31
	s_mov_b32 m0, s55
	v_lshl_add_u64 v[162:163], s[46:47], 0, v[148:149]
	global_load_lds_dwordx4 v148, s[96:97]
	v_lshl_add_u64 v[166:167], s[96:97], 0, v[148:149]
	s_barrier
	s_waitcnt lgkmcnt(0)
	v_mfma_f32_16x16x32_f16 v[122:125], v[202:205], v[170:173], v[122:125]
	v_mfma_f32_16x16x32_f16 v[126:129], v[210:213], v[170:173], v[126:129]
	v_mfma_f32_16x16x32_f16 v[114:117], v[202:205], v[178:181], v[114:117]
	v_mfma_f32_16x16x32_f16 v[118:121], v[210:213], v[178:181], v[118:121]
	v_mfma_f32_16x16x32_f16 v[106:109], v[202:205], v[186:189], v[106:109]
	v_mfma_f32_16x16x32_f16 v[110:113], v[210:213], v[186:189], v[110:113]
	v_mfma_f32_16x16x32_f16 v[98:101], v[202:205], v[194:197], v[98:101]
	v_mfma_f32_16x16x32_f16 v[102:105], v[210:213], v[194:197], v[102:105]
	v_mfma_f32_16x16x32_f16 v[122:125], v[206:209], v[174:177], v[122:125]
	v_mfma_f32_16x16x32_f16 v[126:129], v[214:217], v[174:177], v[126:129]
	v_mfma_f32_16x16x32_f16 v[114:117], v[206:209], v[182:185], v[114:117]
	v_mfma_f32_16x16x32_f16 v[118:121], v[214:217], v[182:185], v[118:121]
	v_mfma_f32_16x16x32_f16 v[106:109], v[206:209], v[190:193], v[106:109]
	v_mfma_f32_16x16x32_f16 v[110:113], v[214:217], v[190:193], v[110:113]
	v_mfma_f32_16x16x32_f16 v[98:101], v[206:209], v[198:201], v[98:101]
	v_mfma_f32_16x16x32_f16 v[102:105], v[214:217], v[198:201], v[102:105]
	s_barrier
	s_mov_b32 m0, s51
	v_lshl_add_u64 v[218:219], s[94:95], 0, v[146:147]
	s_cmp_lg_u32 s100, 1
	s_cbranch_scc1 .Ldef_A_skip
	s_mov_b64 vcc, 0x30000
	v_cvt_pk_f16_f32 v242, v34, v35
	v_cvt_pk_f16_f32 v243, v36, v37
	v_cvt_pk_f16_f32 v244, v38, v39
	v_cvt_pk_f16_f32 v245, v40, v41
	global_store_dwordx4 v[240:241], v[242:245], off nt
	v_cvt_pk_f16_f32 v246, v18, v19
	v_cvt_pk_f16_f32 v247, v20, v21
	v_cvt_pk_f16_f32 v248, v22, v23
	v_cvt_pk_f16_f32 v249, v24, v25
	v_lshl_add_u64 v[250:251], v[240:241], 0, vcc
	global_store_dwordx4 v[250:251], v[246:249], off nt
	v_cvt_pk_f16_f32 v242, v10, v11
	v_cvt_pk_f16_f32 v243, v12, v13
	v_cvt_pk_f16_f32 v244, v14, v15
	v_cvt_pk_f16_f32 v245, v16, v17
	v_lshl_add_u64 v[252:253], v[250:251], 0, vcc
	global_store_dwordx4 v[252:253], v[242:245], off nt
	v_cvt_pk_f16_f32 v246, v2, v3
	v_cvt_pk_f16_f32 v247, v4, v5
	v_cvt_pk_f16_f32 v248, v6, v7
	v_cvt_pk_f16_f32 v249, v8, v9
	v_lshl_add_u64 v[250:251], v[252:253], 0, vcc
	global_store_dwordx4 v[250:251], v[246:249], off nt
	v_mov_b64_e32 v[2:3], 0
	v_mov_b64_e32 v[4:5], 0
	v_mov_b64_e32 v[6:7], 0
	v_mov_b64_e32 v[8:9], 0
	v_mov_b64_e32 v[10:11], 0
	v_mov_b64_e32 v[12:13], 0
	v_mov_b64_e32 v[14:15], 0
	v_mov_b64_e32 v[16:17], 0
	v_mov_b64_e32 v[18:19], 0
	v_mov_b64_e32 v[20:21], 0
	v_mov_b64_e32 v[22:23], 0
	v_mov_b64_e32 v[24:25], 0
	v_mov_b64_e32 v[34:35], 0
	v_mov_b64_e32 v[36:37], 0
	v_mov_b64_e32 v[38:39], 0
	v_mov_b64_e32 v[40:41], 0
; DI unsigned pk2(float a, float b) { typedef _Float16 h2 __attribute__((ext_vector_type(2))); h2 v; v[0] = (f16)a; v[1] = (f16)b; return __builtin_bit_cast(unsigned, v); }
;   DI void operator()(const f32x4 (&acc)[2][2][4][2], const GUnit& u, int wr, int wc, int fr, int fq) const {
;     ...
; #pragma unroll
;     for (int ai = 0; ai < 2; ++ai)
; #pragma unroll
;       for (int m = 0; m < 4; ++m) {
;         f16* zp = base + (size_t)(row0 + ai * 128 + m * 16) * ld + u.pn * 256 + 32 * wc + 8 * fq;
; #pragma unroll
;         for (int bj = 0; bj < 2; ++bj) {
;           f32x4 v0 = acc[ai][bj][m][0], v1 = acc[ai][bj][m][1];
;           if (seg == 5) { v0 *= QSCALE; v1 *= QSCALE; }
;           u32x4_ w; w.x = pk2(v0[0], v0[1]); w.y = pk2(v0[2], v0[3]); w.z = pk2(v1[0], v1[1]); w.w = pk2(v1[2], v1[3]);
;           __builtin_nontemporal_store(w, (u32x4_*)(zp + bj * 128));
;         }
.Ldef_A_skip:
	ds_read_b128 v[170:173], v165 offset:16384
	ds_read_b128 v[174:177], v165 offset:17408
	ds_read_b128 v[178:181], v165 offset:18432
	ds_read_b128 v[182:185], v165 offset:19456
	ds_read_b128 v[186:189], v165 offset:20480
	ds_read_b128 v[190:193], v165 offset:21504
	ds_read_b128 v[194:197], v165 offset:22528
	ds_read_b128 v[198:201], v165 offset:23552
	global_load_lds_dwordx4 v[218:219], off
	v_lshl_add_u64 v[220:221], v[218:219], 0, s[0:1]
	s_mov_b32 m0, s56
	s_nop 0
	global_load_lds_dwordx4 v[220:221], off
	s_barrier
	s_waitcnt lgkmcnt(0)
	v_mfma_f32_16x16x32_f16 v[34:37], v[130:133], v[170:173], v[34:37]
	v_mfma_f32_16x16x32_f16 v[38:41], v[138:141], v[170:173], v[38:41]
	v_mfma_f32_16x16x32_f16 v[18:21], v[130:133], v[178:181], v[18:21]
	v_mfma_f32_16x16x32_f16 v[22:25], v[138:141], v[178:181], v[22:25]
	v_mfma_f32_16x16x32_f16 v[10:13], v[130:133], v[186:189], v[10:13]
	v_mfma_f32_16x16x32_f16 v[14:17], v[138:141], v[186:189], v[14:17]
	v_mfma_f32_16x16x32_f16 v[2:5], v[130:133], v[194:197], v[2:5]
	v_mfma_f32_16x16x32_f16 v[6:9], v[138:141], v[194:197], v[6:9]
	v_mfma_f32_16x16x32_f16 v[34:37], v[134:137], v[174:177], v[34:37]
	v_mfma_f32_16x16x32_f16 v[38:41], v[142:145], v[174:177], v[38:41]
	v_mfma_f32_16x16x32_f16 v[18:21], v[134:137], v[182:185], v[18:21]
	v_mfma_f32_16x16x32_f16 v[22:25], v[142:145], v[182:185], v[22:25]
	v_mfma_f32_16x16x32_f16 v[10:13], v[134:137], v[190:193], v[10:13]
	v_mfma_f32_16x16x32_f16 v[14:17], v[142:145], v[190:193], v[14:17]
	v_mfma_f32_16x16x32_f16 v[2:5], v[134:137], v[198:201], v[2:5]
	v_mfma_f32_16x16x32_f16 v[6:9], v[142:145], v[198:201], v[6:9]
	s_barrier
	s_add_u32 s44, s44, 0x100
	s_addc_u32 s45, s45, 0
	s_add_u32 s91, s91, 0x100
	s_addc_u32 s92, s92, 0
	s_cmp_lg_u32 s100, 1
	s_cbranch_scc1 .Ldef_B_skip
	s_mov_b64 vcc, 0x30000
	v_cvt_pk_f16_f32 v242, v90, v91
	v_cvt_pk_f16_f32 v243, v92, v93
	v_cvt_pk_f16_f32 v244, v94, v95
	v_cvt_pk_f16_f32 v245, v96, v97
	global_store_dwordx4 v[240:241], v[242:245], off offset:256 nt
	v_cvt_pk_f16_f32 v246, v82, v83
	v_cvt_pk_f16_f32 v247, v84, v85
	v_cvt_pk_f16_f32 v248, v86, v87
	v_cvt_pk_f16_f32 v249, v88, v89
	v_lshl_add_u64 v[250:251], v[240:241], 0, vcc
	global_store_dwordx4 v[250:251], v[246:249], off offset:256 nt
	v_cvt_pk_f16_f32 v242, v74, v75
	v_cvt_pk_f16_f32 v243, v76, v77
	v_cvt_pk_f16_f32 v244, v78, v79
	v_cvt_pk_f16_f32 v245, v80, v81
	v_lshl_add_u64 v[252:253], v[250:251], 0, vcc
	global_store_dwordx4 v[252:253], v[242:245], off offset:256 nt
	v_cvt_pk_f16_f32 v246, v70, v71
	v_cvt_pk_f16_f32 v247, v72, v73
	v_cvt_pk_f16_f32 v248, v66, v67
	v_cvt_pk_f16_f32 v249, v68, v69
	v_lshl_add_u64 v[250:251], v[252:253], 0, vcc
	global_store_dwordx4 v[250:251], v[246:249], off offset:256 nt
	v_mov_b64_e32 v[66:67], 0
	v_mov_b64_e32 v[68:69], 0
	v_mov_b64_e32 v[70:71], 0
	v_mov_b64_e32 v[72:73], 0
	v_mov_b64_e32 v[74:75], 0
	v_mov_b64_e32 v[76:77], 0
	v_mov_b64_e32 v[78:79], 0
	v_mov_b64_e32 v[80:81], 0
	v_mov_b64_e32 v[82:83], 0
	v_mov_b64_e32 v[84:85], 0
	v_mov_b64_e32 v[86:87], 0
	v_mov_b64_e32 v[88:89], 0
	v_mov_b64_e32 v[90:91], 0
	v_mov_b64_e32 v[92:93], 0
	v_mov_b64_e32 v[94:95], 0
	v_mov_b64_e32 v[96:97], 0
	s_mov_b32 s100, 0

.Lpl_wdone:
	s_barrier
	v_mfma_f32_16x16x32_f16 v[90:93], v[202:205], v[170:173], v[90:93]
	v_mfma_f32_16x16x32_f16 v[94:97], v[210:213], v[170:173], v[94:97]
	v_mfma_f32_16x16x32_f16 v[82:85], v[202:205], v[178:181], v[82:85]
	v_mfma_f32_16x16x32_f16 v[86:89], v[210:213], v[178:181], v[86:89]
	v_mfma_f32_16x16x32_f16 v[74:77], v[202:205], v[186:189], v[74:77]
	v_mfma_f32_16x16x32_f16 v[78:81], v[210:213], v[186:189], v[78:81]
	v_mfma_f32_16x16x32_f16 v[70:73], v[202:205], v[194:197], v[70:73]
	v_mfma_f32_16x16x32_f16 v[66:69], v[210:213], v[194:197], v[66:69]
	v_mfma_f32_16x16x32_f16 v[90:93], v[206:209], v[174:177], v[90:93]
	v_mfma_f32_16x16x32_f16 v[94:97], v[214:217], v[174:177], v[94:97]
	v_mfma_f32_16x16x32_f16 v[82:85], v[206:209], v[182:185], v[82:85]
	v_mfma_f32_16x16x32_f16 v[86:89], v[214:217], v[182:185], v[86:89]
	v_mfma_f32_16x16x32_f16 v[74:77], v[206:209], v[190:193], v[74:77]
	v_mfma_f32_16x16x32_f16 v[78:81], v[214:217], v[190:193], v[78:81]
	v_mfma_f32_16x16x32_f16 v[70:73], v[206:209], v[198:201], v[70:73]
	v_mfma_f32_16x16x32_f16 v[66:69], v[214:217], v[198:201], v[66:69]
	s_barrier
	ds_read_b128 v[130:133], v254 offset:32768
	ds_read_b128 v[134:137], v254 offset:33792
	ds_read_b128 v[138:141], v254 offset:34816
	ds_read_b128 v[142:145], v254 offset:35840
	s_mov_b32 m0, s61
	v_lshl_add_u64 v[202:203], v[218:219], 0, s[8:9]
	ds_read_b128 v[170:173], v165 offset:32768
	ds_read_b128 v[174:177], v165 offset:33792
	ds_read_b128 v[178:181], v165 offset:34816
	ds_read_b128 v[182:185], v165 offset:35840
	ds_read_b128 v[186:189], v165 offset:36864
	ds_read_b128 v[190:193], v165 offset:37888
	ds_read_b128 v[194:197], v165 offset:38912
	ds_read_b128 v[198:201], v165 offset:39936
	global_load_lds_dwordx4 v[202:203], off
	v_lshl_add_u64 v[202:203], v[218:219], 0, s[12:13]
	s_mov_b32 m0, s62
	s_nop 0
	global_load_lds_dwordx4 v[202:203], off
	s_waitcnt lgkmcnt(8)
	s_barrier
	s_waitcnt lgkmcnt(0)
	v_mfma_f32_16x16x32_f16 v[58:61], v[130:133], v[170:173], v[58:61]
	v_mfma_f32_16x16x32_f16 v[62:65], v[138:141], v[170:173], v[62:65]
	v_mfma_f32_16x16x32_f16 v[50:53], v[130:133], v[178:181], v[50:53]
	v_mfma_f32_16x16x32_f16 v[54:57], v[138:141], v[178:181], v[54:57]
	v_mfma_f32_16x16x32_f16 v[42:45], v[130:133], v[186:189], v[42:45]
	v_mfma_f32_16x16x32_f16 v[46:49], v[138:141], v[186:189], v[46:49]
	v_mfma_f32_16x16x32_f16 v[26:29], v[130:133], v[194:197], v[26:29]
	v_mfma_f32_16x16x32_f16 v[30:33], v[138:141], v[194:197], v[30:33]
	v_mfma_f32_16x16x32_f16 v[58:61], v[134:137], v[174:177], v[58:61]
	v_mfma_f32_16x16x32_f16 v[62:65], v[142:145], v[174:177], v[62:65]
	v_mfma_f32_16x16x32_f16 v[50:53], v[134:137], v[182:185], v[50:53]
	v_mfma_f32_16x16x32_f16 v[54:57], v[142:145], v[182:185], v[54:57]
	v_mfma_f32_16x16x32_f16 v[42:45], v[134:137], v[190:193], v[42:45]
	v_mfma_f32_16x16x32_f16 v[46:49], v[142:145], v[190:193], v[46:49]
	v_mfma_f32_16x16x32_f16 v[26:29], v[134:137], v[198:201], v[26:29]
	v_mfma_f32_16x16x32_f16 v[30:33], v[142:145], v[198:201], v[30:33]
	s_barrier
	s_mov_b32 m0, s63
	ds_read_b128 v[202:205], v254 offset:49152
	ds_read_b128 v[206:209], v254 offset:50176
	v_lshl_add_u64 v[162:163], v[162:163], 0, s[14:15]
	ds_read_b128 v[210:213], v254 offset:51200
	ds_read_b128 v[214:217], v254 offset:52224
	global_load_lds_dwordx4 v[162:163], off
	v_lshl_add_u64 v[162:163], v[166:167], 0, s[14:15]
	s_mov_b32 m0, s64
	s_nop 0
	global_load_lds_dwordx4 v[162:163], off
	s_barrier
; template <bool PEEL, class Sched, class Epi>
; DI void gemm_stream(LAS unsigned char* lds, int K, long lda, long ldb, const Sched& S, const Epi& E) {
;     ...
;     if (PEEL) { GS_TRIP(0, 1); for (int t = 2; t < nt; t += 2) { GS_TRIP(t, 0); } }
	s_waitcnt lgkmcnt(0)
	v_mfma_f32_16x16x32_f16 v[122:125], v[202:205], v[170:173], v[122:125]
	v_mfma_f32_16x16x32_f16 v[126:129], v[210:213], v[170:173], v[126:129]
	v_mfma_f32_16x16x32_f16 v[114:117], v[202:205], v[178:181], v[114:117]
	v_mfma_f32_16x16x32_f16 v[118:121], v[210:213], v[178:181], v[118:121]
	v_mfma_f32_16x16x32_f16 v[106:109], v[202:205], v[186:189], v[106:109]
	v_mfma_f32_16x16x32_f16 v[110:113], v[210:213], v[186:189], v[110:113]
	v_mfma_f32_16x16x32_f16 v[98:101], v[202:205], v[194:197], v[98:101]
	v_mfma_f32_16x16x32_f16 v[102:105], v[210:213], v[194:197], v[102:105]
	v_mfma_f32_16x16x32_f16 v[122:125], v[206:209], v[174:177], v[122:125]
	v_mfma_f32_16x16x32_f16 v[126:129], v[214:217], v[174:177], v[126:129]
	v_mfma_f32_16x16x32_f16 v[114:117], v[206:209], v[182:185], v[114:117]
	v_mfma_f32_16x16x32_f16 v[118:121], v[214:217], v[182:185], v[118:121]
	v_mfma_f32_16x16x32_f16 v[106:109], v[206:209], v[190:193], v[106:109]
	v_mfma_f32_16x16x32_f16 v[110:113], v[214:217], v[190:193], v[110:113]
	v_mfma_f32_16x16x32_f16 v[98:101], v[206:209], v[198:201], v[98:101]
	v_mfma_f32_16x16x32_f16 v[102:105], v[214:217], v[198:201], v[102:105]
	s_barrier
	s_mov_b32 m0, s65
	v_lshl_add_u64 v[162:163], v[218:219], 0, s[14:15]
	ds_read_b128 v[170:173], v165 offset:49152
	ds_read_b128 v[174:177], v165 offset:50176
	ds_read_b128 v[178:181], v165 offset:51200
	ds_read_b128 v[182:185], v165 offset:52224
	ds_read_b128 v[186:189], v165 offset:53248
	ds_read_b128 v[190:193], v165 offset:54272
	ds_read_b128 v[194:197], v165 offset:55296
	ds_read_b128 v[198:201], v165 offset:56320
	global_load_lds_dwordx4 v[162:163], off
	v_lshl_add_u64 v[162:163], v[218:219], 0, s[16:17]
	s_mov_b32 m0, s72
	s_nop 0
	global_load_lds_dwordx4 v[162:163], off
	s_barrier
	s_waitcnt lgkmcnt(0)
	v_mfma_f32_16x16x32_f16 v[34:37], v[130:133], v[170:173], v[34:37]
	v_mfma_f32_16x16x32_f16 v[38:41], v[138:141], v[170:173], v[38:41]
	v_mfma_f32_16x16x32_f16 v[18:21], v[130:133], v[178:181], v[18:21]
	v_mfma_f32_16x16x32_f16 v[22:25], v[138:141], v[178:181], v[22:25]
	v_mfma_f32_16x16x32_f16 v[10:13], v[130:133], v[186:189], v[10:13]
	v_mfma_f32_16x16x32_f16 v[14:17], v[138:141], v[186:189], v[14:17]
	v_mfma_f32_16x16x32_f16 v[2:5], v[130:133], v[194:197], v[2:5]
	v_mfma_f32_16x16x32_f16 v[6:9], v[138:141], v[194:197], v[6:9]
	v_mfma_f32_16x16x32_f16 v[34:37], v[134:137], v[174:177], v[34:37]
	v_mfma_f32_16x16x32_f16 v[38:41], v[142:145], v[174:177], v[38:41]
	v_mfma_f32_16x16x32_f16 v[18:21], v[134:137], v[182:185], v[18:21]
	v_mfma_f32_16x16x32_f16 v[22:25], v[142:145], v[182:185], v[22:25]
	v_mfma_f32_16x16x32_f16 v[10:13], v[134:137], v[190:193], v[10:13]
	v_mfma_f32_16x16x32_f16 v[14:17], v[142:145], v[190:193], v[14:17]
	v_mfma_f32_16x16x32_f16 v[2:5], v[134:137], v[198:201], v[2:5]
	v_mfma_f32_16x16x32_f16 v[6:9], v[142:145], v[198:201], v[6:9]
	s_barrier
	s_mov_b32 m0, s73
	v_lshl_add_u64 v[130:131], v[220:221], 0, s[14:15]
	global_load_lds_dwordx4 v[130:131], off
	v_lshl_add_u64 v[130:131], v[222:223], 0, s[14:15]
	s_mov_b32 m0, s74
	s_nop 0
	global_load_lds_dwordx4 v[130:131], off
	s_waitcnt vmcnt(6)
	s_barrier
	v_mfma_f32_16x16x32_f16 v[90:93], v[202:205], v[170:173], v[90:93]
	v_mfma_f32_16x16x32_f16 v[94:97], v[210:213], v[170:173], v[94:97]
	v_mfma_f32_16x16x32_f16 v[82:85], v[202:205], v[178:181], v[82:85]
	v_mfma_f32_16x16x32_f16 v[86:89], v[210:213], v[178:181], v[86:89]
	v_mfma_f32_16x16x32_f16 v[74:77], v[202:205], v[186:189], v[74:77]
	v_mfma_f32_16x16x32_f16 v[78:81], v[210:213], v[186:189], v[78:81]
	v_mfma_f32_16x16x32_f16 v[70:73], v[202:205], v[194:197], v[70:73]
	v_mfma_f32_16x16x32_f16 v[66:69], v[210:213], v[194:197], v[66:69]
	v_mfma_f32_16x16x32_f16 v[90:93], v[206:209], v[174:177], v[90:93]
	v_mfma_f32_16x16x32_f16 v[94:97], v[214:217], v[174:177], v[94:97]
	v_mfma_f32_16x16x32_f16 v[82:85], v[206:209], v[182:185], v[82:85]
	v_mfma_f32_16x16x32_f16 v[86:89], v[214:217], v[182:185], v[86:89]
	v_mfma_f32_16x16x32_f16 v[74:77], v[206:209], v[190:193], v[74:77]
	v_mfma_f32_16x16x32_f16 v[78:81], v[214:217], v[190:193], v[78:81]
	v_mfma_f32_16x16x32_f16 v[70:73], v[206:209], v[198:201], v[70:73]
	v_mfma_f32_16x16x32_f16 v[66:69], v[214:217], v[198:201], v[66:69]
	s_add_i32 s93, s93, 2
	s_cmp_gt_u32 s93, 13
	s_barrier
	s_cbranch_scc1 .LBB0_264

.Lgb_body:
	s_add_u32 s94, s44, 0xfffc0080
	s_addc_u32 s95, s45, -1
	s_and_b64 s[46:47], s[46:47], exec
	s_cselect_b32 s95, s29, s95
	s_cselect_b32 s94, s43, s94
	s_cselect_b32 s47, s89, s92
	s_cselect_b32 s46, s90, s91
.Lgb_body2:
	ds_read_b128 v[130:133], v254
	ds_read_b128 v[134:137], v254 offset:1024
	ds_read_b128 v[138:141], v254 offset:2048
	ds_read_b128 v[142:145], v254 offset:3072
	s_mov_b32 m0, s79
	s_add_u32 s98, s44, s0
	s_addc_u32 s99, s45, s1
	ds_read_b128 v[170:173], v165
	ds_read_b128 v[174:177], v165 offset:1024
	ds_read_b128 v[178:181], v165 offset:2048
	ds_read_b128 v[182:185], v165 offset:3072
	ds_read_b128 v[186:189], v165 offset:4096
	ds_read_b128 v[190:193], v165 offset:5120
	ds_read_b128 v[194:197], v165 offset:6144
	ds_read_b128 v[198:201], v165 offset:7168
	global_load_lds_dwordx4 v160, s[44:45]
	s_mov_b32 m0, s80
	s_nop 0
	global_load_lds_dwordx4 v160, s[98:99]
	s_waitcnt lgkmcnt(8)
	s_barrier
	s_waitcnt lgkmcnt(0)
	v_mfma_f32_16x16x32_f16 v[58:61], v[130:133], v[170:173], v[58:61]
	v_mfma_f32_16x16x32_f16 v[62:65], v[138:141], v[170:173], v[62:65]
	v_mfma_f32_16x16x32_f16 v[50:53], v[130:133], v[178:181], v[50:53]
	v_mfma_f32_16x16x32_f16 v[54:57], v[138:141], v[178:181], v[54:57]
	v_mfma_f32_16x16x32_f16 v[42:45], v[130:133], v[186:189], v[42:45]
	v_mfma_f32_16x16x32_f16 v[46:49], v[138:141], v[186:189], v[46:49]
	v_mfma_f32_16x16x32_f16 v[26:29], v[130:133], v[194:197], v[26:29]
	v_mfma_f32_16x16x32_f16 v[30:33], v[138:141], v[194:197], v[30:33]
	v_mfma_f32_16x16x32_f16 v[58:61], v[134:137], v[174:177], v[58:61]
	v_mfma_f32_16x16x32_f16 v[62:65], v[142:145], v[174:177], v[62:65]
	v_mfma_f32_16x16x32_f16 v[50:53], v[134:137], v[182:185], v[50:53]
	v_mfma_f32_16x16x32_f16 v[54:57], v[142:145], v[182:185], v[54:57]
	v_mfma_f32_16x16x32_f16 v[42:45], v[134:137], v[190:193], v[42:45]
	v_mfma_f32_16x16x32_f16 v[46:49], v[142:145], v[190:193], v[46:49]
	v_mfma_f32_16x16x32_f16 v[26:29], v[134:137], v[198:201], v[26:29]
	v_mfma_f32_16x16x32_f16 v[30:33], v[142:145], v[198:201], v[30:33]
	s_barrier
	s_mov_b32 m0, s54
	ds_read_b128 v[202:205], v254 offset:16384
	ds_read_b128 v[206:209], v254 offset:17408
	s_add_u32 s96, s46, s30
	ds_read_b128 v[210:213], v254 offset:18432
	ds_read_b128 v[214:217], v254 offset:19456
	global_load_lds_dwordx4 v148, s[46:47]
	s_addc_u32 s97, s47, s31
	s_mov_b32 m0, s55
	global_load_lds_dwordx4 v148, s[96:97]
	s_barrier
	s_waitcnt lgkmcnt(0)
	v_mfma_f32_16x16x32_f16 v[122:125], v[202:205], v[170:173], v[122:125]
	v_mfma_f32_16x16x32_f16 v[126:129], v[210:213], v[170:173], v[126:129]
	v_mfma_f32_16x16x32_f16 v[114:117], v[202:205], v[178:181], v[114:117]
	v_mfma_f32_16x16x32_f16 v[118:121], v[210:213], v[178:181], v[118:121]
	v_mfma_f32_16x16x32_f16 v[106:109], v[202:205], v[186:189], v[106:109]
	v_mfma_f32_16x16x32_f16 v[110:113], v[210:213], v[186:189], v[110:113]
	v_mfma_f32_16x16x32_f16 v[98:101], v[202:205], v[194:197], v[98:101]
	v_mfma_f32_16x16x32_f16 v[102:105], v[210:213], v[194:197], v[102:105]
	v_mfma_f32_16x16x32_f16 v[122:125], v[206:209], v[174:177], v[122:125]
	v_mfma_f32_16x16x32_f16 v[126:129], v[214:217], v[174:177], v[126:129]
	v_mfma_f32_16x16x32_f16 v[114:117], v[206:209], v[182:185], v[114:117]
	v_mfma_f32_16x16x32_f16 v[118:121], v[214:217], v[182:185], v[118:121]
	v_mfma_f32_16x16x32_f16 v[106:109], v[206:209], v[190:193], v[106:109]
	v_mfma_f32_16x16x32_f16 v[110:113], v[214:217], v[190:193], v[110:113]
	v_mfma_f32_16x16x32_f16 v[98:101], v[206:209], v[198:201], v[98:101]
	v_mfma_f32_16x16x32_f16 v[102:105], v[214:217], v[198:201], v[102:105]
	s_barrier
	s_mov_b32 m0, s51
	s_add_u32 s98, s94, s0
	s_addc_u32 s99, s95, s1
	ds_read_b128 v[170:173], v165 offset:16384
	ds_read_b128 v[174:177], v165 offset:17408
	ds_read_b128 v[178:181], v165 offset:18432
	ds_read_b128 v[182:185], v165 offset:19456
	ds_read_b128 v[186:189], v165 offset:20480
	ds_read_b128 v[190:193], v165 offset:21504
	ds_read_b128 v[194:197], v165 offset:22528
	ds_read_b128 v[198:201], v165 offset:23552
	global_load_lds_dwordx4 v146, s[94:95]
	s_mov_b32 m0, s56
	s_nop 0
	global_load_lds_dwordx4 v146, s[98:99]
	s_barrier
	s_waitcnt lgkmcnt(0)
	v_mfma_f32_16x16x32_f16 v[34:37], v[130:133], v[170:173], v[34:37]
	v_mfma_f32_16x16x32_f16 v[38:41], v[138:141], v[170:173], v[38:41]
	v_mfma_f32_16x16x32_f16 v[18:21], v[130:133], v[178:181], v[18:21]
	v_mfma_f32_16x16x32_f16 v[22:25], v[138:141], v[178:181], v[22:25]
	v_mfma_f32_16x16x32_f16 v[10:13], v[130:133], v[186:189], v[10:13]
	v_mfma_f32_16x16x32_f16 v[14:17], v[138:141], v[186:189], v[14:17]
	v_mfma_f32_16x16x32_f16 v[2:5], v[130:133], v[194:197], v[2:5]
	v_mfma_f32_16x16x32_f16 v[6:9], v[138:141], v[194:197], v[6:9]
	v_mfma_f32_16x16x32_f16 v[34:37], v[134:137], v[174:177], v[34:37]
	v_mfma_f32_16x16x32_f16 v[38:41], v[142:145], v[174:177], v[38:41]
	v_mfma_f32_16x16x32_f16 v[18:21], v[134:137], v[182:185], v[18:21]
	v_mfma_f32_16x16x32_f16 v[22:25], v[142:145], v[182:185], v[22:25]
	v_mfma_f32_16x16x32_f16 v[10:13], v[134:137], v[190:193], v[10:13]
	v_mfma_f32_16x16x32_f16 v[14:17], v[142:145], v[190:193], v[14:17]
	v_mfma_f32_16x16x32_f16 v[2:5], v[134:137], v[198:201], v[2:5]
	v_mfma_f32_16x16x32_f16 v[6:9], v[142:145], v[198:201], v[6:9]
	s_barrier
	s_add_u32 s44, s44, 0x100
	s_addc_u32 s45, s45, 0
	s_add_u32 s91, s91, 0x100
	s_addc_u32 s92, s92, 0
	s_add_u32 s46, s46, s18
	s_addc_u32 s47, s47, s19
	s_mov_b32 m0, s57
	global_load_lds_dwordx4 v148, s[46:47]
	s_add_u32 s46, s46, s30
	s_addc_u32 s47, s47, s31
	s_mov_b32 m0, s60
	global_load_lds_dwordx4 v148, s[46:47]
	s_waitcnt vmcnt(6)
	s_barrier
	v_mfma_f32_16x16x32_f16 v[90:93], v[202:205], v[170:173], v[90:93]
	v_mfma_f32_16x16x32_f16 v[94:97], v[210:213], v[170:173], v[94:97]
	v_mfma_f32_16x16x32_f16 v[82:85], v[202:205], v[178:181], v[82:85]
	v_mfma_f32_16x16x32_f16 v[86:89], v[210:213], v[178:181], v[86:89]
	v_mfma_f32_16x16x32_f16 v[74:77], v[202:205], v[186:189], v[74:77]
	v_mfma_f32_16x16x32_f16 v[78:81], v[210:213], v[186:189], v[78:81]
	v_mfma_f32_16x16x32_f16 v[70:73], v[202:205], v[194:197], v[70:73]
	v_mfma_f32_16x16x32_f16 v[66:69], v[210:213], v[194:197], v[66:69]
	v_mfma_f32_16x16x32_f16 v[90:93], v[206:209], v[174:177], v[90:93]
	v_mfma_f32_16x16x32_f16 v[94:97], v[214:217], v[174:177], v[94:97]
	v_mfma_f32_16x16x32_f16 v[82:85], v[206:209], v[182:185], v[82:85]
	v_mfma_f32_16x16x32_f16 v[86:89], v[214:217], v[182:185], v[86:89]
	v_mfma_f32_16x16x32_f16 v[74:77], v[206:209], v[190:193], v[74:77]
	v_mfma_f32_16x16x32_f16 v[78:81], v[214:217], v[190:193], v[78:81]
	v_mfma_f32_16x16x32_f16 v[70:73], v[206:209], v[198:201], v[70:73]
	v_mfma_f32_16x16x32_f16 v[66:69], v[214:217], v[198:201], v[66:69]
	s_barrier
	ds_read_b128 v[130:133], v254 offset:32768
	ds_read_b128 v[134:137], v254 offset:33792
	ds_read_b128 v[138:141], v254 offset:34816
	ds_read_b128 v[142:145], v254 offset:35840
	s_mov_b32 m0, s61
	s_add_u32 s98, s94, s8
	s_addc_u32 s99, s95, s9
	ds_read_b128 v[170:173], v165 offset:32768
	ds_read_b128 v[174:177], v165 offset:33792
	ds_read_b128 v[178:181], v165 offset:34816
	ds_read_b128 v[182:185], v165 offset:35840
	ds_read_b128 v[186:189], v165 offset:36864
	ds_read_b128 v[190:193], v165 offset:37888
	ds_read_b128 v[194:197], v165 offset:38912
	ds_read_b128 v[198:201], v165 offset:39936
	global_load_lds_dwordx4 v146, s[98:99]
	s_add_u32 s98, s94, s12
	s_addc_u32 s99, s95, s13
	s_mov_b32 m0, s62
	s_nop 0
	global_load_lds_dwordx4 v146, s[98:99]
	s_waitcnt lgkmcnt(8)
	s_barrier
	s_waitcnt lgkmcnt(0)
	v_mfma_f32_16x16x32_f16 v[58:61], v[130:133], v[170:173], v[58:61]
	v_mfma_f32_16x16x32_f16 v[62:65], v[138:141], v[170:173], v[62:65]
	v_mfma_f32_16x16x32_f16 v[50:53], v[130:133], v[178:181], v[50:53]
	v_mfma_f32_16x16x32_f16 v[54:57], v[138:141], v[178:181], v[54:57]
	v_mfma_f32_16x16x32_f16 v[42:45], v[130:133], v[186:189], v[42:45]
	v_mfma_f32_16x16x32_f16 v[46:49], v[138:141], v[186:189], v[46:49]
	v_mfma_f32_16x16x32_f16 v[26:29], v[130:133], v[194:197], v[26:29]
	v_mfma_f32_16x16x32_f16 v[30:33], v[138:141], v[194:197], v[30:33]
	v_mfma_f32_16x16x32_f16 v[58:61], v[134:137], v[174:177], v[58:61]
	v_mfma_f32_16x16x32_f16 v[62:65], v[142:145], v[174:177], v[62:65]
	v_mfma_f32_16x16x32_f16 v[50:53], v[134:137], v[182:185], v[50:53]
	v_mfma_f32_16x16x32_f16 v[54:57], v[142:145], v[182:185], v[54:57]
	v_mfma_f32_16x16x32_f16 v[42:45], v[134:137], v[190:193], v[42:45]
	v_mfma_f32_16x16x32_f16 v[46:49], v[142:145], v[190:193], v[46:49]
	v_mfma_f32_16x16x32_f16 v[26:29], v[134:137], v[198:201], v[26:29]
	v_mfma_f32_16x16x32_f16 v[30:33], v[142:145], v[198:201], v[30:33]
	s_barrier
	s_mov_b32 m0, s63
	ds_read_b128 v[202:205], v254 offset:49152
	ds_read_b128 v[206:209], v254 offset:50176
	s_add_u32 s96, s96, s14
	s_addc_u32 s97, s97, s15
	s_sub_u32 s98, s96, s30
	s_subb_u32 s99, s97, s31
	ds_read_b128 v[210:213], v254 offset:51200
	ds_read_b128 v[214:217], v254 offset:52224
	global_load_lds_dwordx4 v148, s[98:99]
	s_mov_b32 m0, s64
	s_nop 0
	global_load_lds_dwordx4 v148, s[96:97]
	s_barrier
	s_waitcnt lgkmcnt(0)
	v_mfma_f32_16x16x32_f16 v[122:125], v[202:205], v[170:173], v[122:125]
	v_mfma_f32_16x16x32_f16 v[126:129], v[210:213], v[170:173], v[126:129]
	v_mfma_f32_16x16x32_f16 v[114:117], v[202:205], v[178:181], v[114:117]
	v_mfma_f32_16x16x32_f16 v[118:121], v[210:213], v[178:181], v[118:121]
	v_mfma_f32_16x16x32_f16 v[106:109], v[202:205], v[186:189], v[106:109]
	v_mfma_f32_16x16x32_f16 v[110:113], v[210:213], v[186:189], v[110:113]
	v_mfma_f32_16x16x32_f16 v[98:101], v[202:205], v[194:197], v[98:101]
	v_mfma_f32_16x16x32_f16 v[102:105], v[210:213], v[194:197], v[102:105]
	v_mfma_f32_16x16x32_f16 v[122:125], v[206:209], v[174:177], v[122:125]
	v_mfma_f32_16x16x32_f16 v[126:129], v[214:217], v[174:177], v[126:129]
	v_mfma_f32_16x16x32_f16 v[114:117], v[206:209], v[182:185], v[114:117]
	v_mfma_f32_16x16x32_f16 v[118:121], v[214:217], v[182:185], v[118:121]
	v_mfma_f32_16x16x32_f16 v[106:109], v[206:209], v[190:193], v[106:109]
	v_mfma_f32_16x16x32_f16 v[110:113], v[214:217], v[190:193], v[110:113]
	v_mfma_f32_16x16x32_f16 v[98:101], v[206:209], v[198:201], v[98:101]
	v_mfma_f32_16x16x32_f16 v[102:105], v[214:217], v[198:201], v[102:105]
	s_barrier
; template <bool PEEL, class Sched, class Epi>
; DI void gemm_stream(LAS unsigned char* lds, int K, long lda, long ldb, const Sched& S, const Epi& E) {
;     ...
;     if (PEEL) { GS_TRIP(0, 1); for (int t = 2; t < nt; t += 2) { GS_TRIP(t, 0); } }
;     else { for (int t = 0; t < nt; t += 2) { GS_TRIP(t, 0); } }
	s_mov_b32 m0, s65
	s_add_u32 s98, s94, s14
	s_addc_u32 s99, s95, s15
	ds_read_b128 v[170:173], v165 offset:49152
	ds_read_b128 v[174:177], v165 offset:50176
	ds_read_b128 v[178:181], v165 offset:51200
	ds_read_b128 v[182:185], v165 offset:52224
	ds_read_b128 v[186:189], v165 offset:53248
	ds_read_b128 v[190:193], v165 offset:54272
	ds_read_b128 v[194:197], v165 offset:55296
	ds_read_b128 v[198:201], v165 offset:56320
	global_load_lds_dwordx4 v146, s[98:99]
	s_add_u32 s98, s94, s16
	s_addc_u32 s99, s95, s17
	s_mov_b32 m0, s72
	s_nop 0
	global_load_lds_dwordx4 v146, s[98:99]
	s_barrier
	s_waitcnt lgkmcnt(0)
	v_mfma_f32_16x16x32_f16 v[34:37], v[130:133], v[170:173], v[34:37]
	v_mfma_f32_16x16x32_f16 v[38:41], v[138:141], v[170:173], v[38:41]
	v_mfma_f32_16x16x32_f16 v[18:21], v[130:133], v[178:181], v[18:21]
	v_mfma_f32_16x16x32_f16 v[22:25], v[138:141], v[178:181], v[22:25]
	v_mfma_f32_16x16x32_f16 v[10:13], v[130:133], v[186:189], v[10:13]
	v_mfma_f32_16x16x32_f16 v[14:17], v[138:141], v[186:189], v[14:17]
	v_mfma_f32_16x16x32_f16 v[2:5], v[130:133], v[194:197], v[2:5]
	v_mfma_f32_16x16x32_f16 v[6:9], v[138:141], v[194:197], v[6:9]
	v_mfma_f32_16x16x32_f16 v[34:37], v[134:137], v[174:177], v[34:37]
	v_mfma_f32_16x16x32_f16 v[38:41], v[142:145], v[174:177], v[38:41]
	v_mfma_f32_16x16x32_f16 v[18:21], v[134:137], v[182:185], v[18:21]
	v_mfma_f32_16x16x32_f16 v[22:25], v[142:145], v[182:185], v[22:25]
	v_mfma_f32_16x16x32_f16 v[10:13], v[134:137], v[190:193], v[10:13]
	v_mfma_f32_16x16x32_f16 v[14:17], v[142:145], v[190:193], v[14:17]
	v_mfma_f32_16x16x32_f16 v[2:5], v[134:137], v[198:201], v[2:5]
	v_mfma_f32_16x16x32_f16 v[6:9], v[142:145], v[198:201], v[6:9]
	s_barrier
	s_mov_b32 m0, s73
	s_add_u32 s46, s46, s14
	s_addc_u32 s47, s47, s15
	s_sub_u32 s98, s46, s30
	s_subb_u32 s99, s47, s31
	global_load_lds_dwordx4 v148, s[98:99]
	s_mov_b32 m0, s74
	s_nop 0
	global_load_lds_dwordx4 v148, s[46:47]
	s_waitcnt vmcnt(6)
	s_barrier
	v_mfma_f32_16x16x32_f16 v[90:93], v[202:205], v[170:173], v[90:93]
	v_mfma_f32_16x16x32_f16 v[94:97], v[210:213], v[170:173], v[94:97]
	v_mfma_f32_16x16x32_f16 v[82:85], v[202:205], v[178:181], v[82:85]
	v_mfma_f32_16x16x32_f16 v[86:89], v[210:213], v[178:181], v[86:89]
	v_mfma_f32_16x16x32_f16 v[74:77], v[202:205], v[186:189], v[74:77]
	v_mfma_f32_16x16x32_f16 v[78:81], v[210:213], v[186:189], v[78:81]
	v_mfma_f32_16x16x32_f16 v[70:73], v[202:205], v[194:197], v[70:73]
	v_mfma_f32_16x16x32_f16 v[66:69], v[210:213], v[194:197], v[66:69]
	v_mfma_f32_16x16x32_f16 v[90:93], v[206:209], v[174:177], v[90:93]
	v_mfma_f32_16x16x32_f16 v[94:97], v[214:217], v[174:177], v[94:97]
	v_mfma_f32_16x16x32_f16 v[82:85], v[206:209], v[182:185], v[82:85]
	v_mfma_f32_16x16x32_f16 v[86:89], v[214:217], v[182:185], v[86:89]
	v_mfma_f32_16x16x32_f16 v[74:77], v[206:209], v[190:193], v[74:77]
	v_mfma_f32_16x16x32_f16 v[78:81], v[214:217], v[190:193], v[78:81]
	v_mfma_f32_16x16x32_f16 v[70:73], v[206:209], v[198:201], v[70:73]
	v_mfma_f32_16x16x32_f16 v[66:69], v[214:217], v[198:201], v[66:69]
	s_add_i32 s93, s93, 2
	s_cmp_gt_u32 s93, 13
	s_barrier
	s_cbranch_scc1 .LBB0_264
	s_cmp_eq_u32 s93, 12
	s_cbranch_scc1 .Lgb_last
	s_add_u32 s94, s44, 0xfffc0080
	s_addc_u32 s95, s45, -1
	s_mov_b32 s47, s92
	s_mov_b32 s46, s91
	s_branch .Lgb_body2
.Lgb_last:
	s_mov_b64 s[46:47], -1
	s_and_b64 s[94:95], s[6:7], s[46:47]
	s_andn2_b64 vcc, exec, s[94:95]
	s_cbranch_vccnz .Lgb_body
	s_branch .Lgb_hdr_rest

.LBB0_843:
	s_add_u32 s86, s44, 0xffe80080
	s_addc_u32 s87, s45, -1
	s_and_b64 s[46:47], s[46:47], exec
	s_cselect_b32 s47, s4, s87
	s_cselect_b32 s46, s43, s86
	s_cselect_b32 s87, s48, s84
	s_cselect_b32 s86, s50, s51
.Lg2_body2:
	ds_read_b128 v[136:139], v254
	ds_read_b128 v[144:147], v254 offset:1024
	ds_read_b128 v[148:151], v254 offset:2048
	ds_read_b128 v[152:155], v254 offset:3072
	s_mov_b32 m0, s79
	ds_read_b128 v[156:159], v141
	ds_read_b128 v[160:163], v141 offset:1024
	ds_read_b128 v[164:167], v141 offset:2048
	ds_read_b128 v[168:171], v141 offset:3072
	ds_read_b128 v[172:175], v141 offset:4096
	ds_read_b128 v[176:179], v141 offset:5120
	ds_read_b128 v[180:183], v141 offset:6144
	ds_read_b128 v[184:187], v141 offset:7168
	global_load_lds_dwordx4 v134, s[44:45]
	s_mov_b32 m0, s80
	s_add_u32 s98, s44, s16
	s_addc_u32 s99, s45, s17
	global_load_lds_dwordx4 v134, s[98:99]
	s_waitcnt lgkmcnt(8)
	s_barrier
	s_waitcnt lgkmcnt(0)
	v_mfma_f32_16x16x32_f16 v[118:121], v[136:139], v[156:159], v[118:121]
	v_mfma_f32_16x16x32_f16 v[114:117], v[148:151], v[156:159], v[114:117]
	v_mfma_f32_16x16x32_f16 v[102:105], v[136:139], v[164:167], v[102:105]
	v_mfma_f32_16x16x32_f16 v[98:101], v[148:151], v[164:167], v[98:101]
	v_mfma_f32_16x16x32_f16 v[86:89], v[136:139], v[172:175], v[86:89]
	v_mfma_f32_16x16x32_f16 v[82:85], v[148:151], v[172:175], v[82:85]
	v_mfma_f32_16x16x32_f16 v[66:69], v[136:139], v[180:183], v[66:69]
	v_mfma_f32_16x16x32_f16 v[54:57], v[148:151], v[180:183], v[54:57]
	v_mfma_f32_16x16x32_f16 v[118:121], v[144:147], v[160:163], v[118:121]
	v_mfma_f32_16x16x32_f16 v[114:117], v[152:155], v[160:163], v[114:117]
	v_mfma_f32_16x16x32_f16 v[102:105], v[144:147], v[168:171], v[102:105]
	v_mfma_f32_16x16x32_f16 v[98:101], v[152:155], v[168:171], v[98:101]
	v_mfma_f32_16x16x32_f16 v[86:89], v[144:147], v[176:179], v[86:89]
	v_mfma_f32_16x16x32_f16 v[82:85], v[152:155], v[176:179], v[82:85]
	v_mfma_f32_16x16x32_f16 v[66:69], v[144:147], v[184:187], v[66:69]
	v_mfma_f32_16x16x32_f16 v[54:57], v[152:155], v[184:187], v[54:57]
	s_barrier
	s_mov_b32 m0, s57
	ds_read_b128 v[188:191], v254 offset:16384
	ds_read_b128 v[192:195], v254 offset:17408
	ds_read_b128 v[196:199], v254 offset:18432
	ds_read_b128 v[200:203], v254 offset:19456
	global_load_lds_dwordx4 v132, s[86:87]
	s_mov_b32 m0, s58
	s_add_u32 s98, s86, s14
	s_addc_u32 s99, s87, s15
	global_load_lds_dwordx4 v132, s[98:99]
	s_barrier
	s_waitcnt lgkmcnt(0)
	v_mfma_f32_16x16x32_f16 v[122:125], v[188:191], v[156:159], v[122:125]
	v_mfma_f32_16x16x32_f16 v[126:129], v[196:199], v[156:159], v[126:129]
	v_mfma_f32_16x16x32_f16 v[106:109], v[188:191], v[164:167], v[106:109]
	v_mfma_f32_16x16x32_f16 v[110:113], v[196:199], v[164:167], v[110:113]
	v_mfma_f32_16x16x32_f16 v[90:93], v[188:191], v[172:175], v[90:93]
	v_mfma_f32_16x16x32_f16 v[94:97], v[196:199], v[172:175], v[94:97]
	v_mfma_f32_16x16x32_f16 v[74:77], v[188:191], v[180:183], v[74:77]
	v_mfma_f32_16x16x32_f16 v[78:81], v[196:199], v[180:183], v[78:81]
	v_mfma_f32_16x16x32_f16 v[122:125], v[192:195], v[160:163], v[122:125]
	v_mfma_f32_16x16x32_f16 v[126:129], v[200:203], v[160:163], v[126:129]
	v_mfma_f32_16x16x32_f16 v[106:109], v[192:195], v[168:171], v[106:109]
	v_mfma_f32_16x16x32_f16 v[110:113], v[200:203], v[168:171], v[110:113]
	v_mfma_f32_16x16x32_f16 v[90:93], v[192:195], v[176:179], v[90:93]
	v_mfma_f32_16x16x32_f16 v[94:97], v[200:203], v[176:179], v[94:97]
	v_mfma_f32_16x16x32_f16 v[74:77], v[192:195], v[184:187], v[74:77]
	v_mfma_f32_16x16x32_f16 v[78:81], v[200:203], v[184:187], v[78:81]
	s_barrier
	s_mov_b32 m0, s56
	ds_read_b128 v[156:159], v141 offset:16384
	ds_read_b128 v[160:163], v141 offset:17408
	ds_read_b128 v[164:167], v141 offset:18432
	ds_read_b128 v[168:171], v141 offset:19456
	ds_read_b128 v[172:175], v141 offset:20480
	ds_read_b128 v[176:179], v141 offset:21504
	ds_read_b128 v[180:183], v141 offset:22528
	ds_read_b128 v[184:187], v141 offset:23552
	global_load_lds_dwordx4 v130, s[46:47]
	s_mov_b32 m0, s59
	s_add_u32 s98, s46, s16
	s_addc_u32 s99, s47, s17
	global_load_lds_dwordx4 v130, s[98:99]
	s_barrier
	s_waitcnt lgkmcnt(0)
	v_mfma_f32_16x16x32_f16 v[58:61], v[136:139], v[156:159], v[58:61]
	v_mfma_f32_16x16x32_f16 v[50:53], v[148:151], v[156:159], v[50:53]
	v_mfma_f32_16x16x32_f16 v[38:41], v[136:139], v[164:167], v[38:41]
	v_mfma_f32_16x16x32_f16 v[34:37], v[148:151], v[164:167], v[34:37]
	v_mfma_f32_16x16x32_f16 v[22:25], v[136:139], v[172:175], v[22:25]
	v_mfma_f32_16x16x32_f16 v[18:21], v[148:151], v[172:175], v[18:21]
	v_mfma_f32_16x16x32_f16 v[10:13], v[136:139], v[180:183], v[10:13]
	v_mfma_f32_16x16x32_f16 v[6:9], v[148:151], v[180:183], v[6:9]
	v_mfma_f32_16x16x32_f16 v[58:61], v[144:147], v[160:163], v[58:61]
	v_mfma_f32_16x16x32_f16 v[50:53], v[152:155], v[160:163], v[50:53]
	v_mfma_f32_16x16x32_f16 v[38:41], v[144:147], v[168:171], v[38:41]
	v_mfma_f32_16x16x32_f16 v[34:37], v[152:155], v[168:171], v[34:37]
	v_mfma_f32_16x16x32_f16 v[22:25], v[144:147], v[176:179], v[22:25]
	v_mfma_f32_16x16x32_f16 v[18:21], v[152:155], v[176:179], v[18:21]
	v_mfma_f32_16x16x32_f16 v[10:13], v[144:147], v[184:187], v[10:13]
	v_mfma_f32_16x16x32_f16 v[6:9], v[152:155], v[184:187], v[6:9]
	s_barrier
	s_add_u32 s44, s44, 0x100
	s_addc_u32 s45, s45, 0
	s_add_u32 s51, s51, 0x100
	s_addc_u32 s84, s84, 0
	s_mov_b32 m0, s60
	s_add_u32 s98, s86, s18
	s_addc_u32 s99, s87, s19
	global_load_lds_dwordx4 v132, s[98:99]
	s_mov_b32 m0, s61
	s_add_u32 s98, s86, s16
	s_addc_u32 s99, s87, s17
	global_load_lds_dwordx4 v132, s[98:99]
	s_waitcnt vmcnt(6)
	s_barrier
	v_mfma_f32_16x16x32_f16 v[62:65], v[188:191], v[156:159], v[62:65]
	v_mfma_f32_16x16x32_f16 v[70:73], v[196:199], v[156:159], v[70:73]
	v_mfma_f32_16x16x32_f16 v[42:45], v[188:191], v[164:167], v[42:45]
	v_mfma_f32_16x16x32_f16 v[46:49], v[196:199], v[164:167], v[46:49]
	v_mfma_f32_16x16x32_f16 v[26:29], v[188:191], v[172:175], v[26:29]
	v_mfma_f32_16x16x32_f16 v[30:33], v[196:199], v[172:175], v[30:33]
	v_mfma_f32_16x16x32_f16 v[14:17], v[188:191], v[180:183], v[14:17]
	v_mfma_f32_16x16x32_f16 v[2:5], v[196:199], v[180:183], v[2:5]
	v_mfma_f32_16x16x32_f16 v[62:65], v[192:195], v[160:163], v[62:65]
	v_mfma_f32_16x16x32_f16 v[70:73], v[200:203], v[160:163], v[70:73]
	v_mfma_f32_16x16x32_f16 v[42:45], v[192:195], v[168:171], v[42:45]
	v_mfma_f32_16x16x32_f16 v[46:49], v[200:203], v[168:171], v[46:49]
	v_mfma_f32_16x16x32_f16 v[26:29], v[192:195], v[176:179], v[26:29]
	v_mfma_f32_16x16x32_f16 v[30:33], v[200:203], v[176:179], v[30:33]
	v_mfma_f32_16x16x32_f16 v[14:17], v[192:195], v[184:187], v[14:17]
	v_mfma_f32_16x16x32_f16 v[2:5], v[200:203], v[184:187], v[2:5]
	s_barrier
	ds_read_b128 v[136:139], v254 offset:32768
	ds_read_b128 v[144:147], v254 offset:33792
	ds_read_b128 v[148:151], v254 offset:34816
	ds_read_b128 v[152:155], v254 offset:35840
	s_mov_b32 m0, s62
	ds_read_b128 v[156:159], v141 offset:32768
	ds_read_b128 v[160:163], v141 offset:33792
	ds_read_b128 v[164:167], v141 offset:34816
	ds_read_b128 v[168:171], v141 offset:35840
	ds_read_b128 v[172:175], v141 offset:36864
	ds_read_b128 v[176:179], v141 offset:37888
	ds_read_b128 v[180:183], v141 offset:38912
	ds_read_b128 v[184:187], v141 offset:39936
	s_add_u32 s98, s46, s20
	s_addc_u32 s99, s47, s21
	global_load_lds_dwordx4 v130, s[98:99]
	s_mov_b32 m0, s63
	s_add_u32 s98, s46, s22
	s_addc_u32 s99, s47, s23
	global_load_lds_dwordx4 v130, s[98:99]
	s_waitcnt lgkmcnt(8)
	s_barrier
	s_waitcnt lgkmcnt(0)
	v_mfma_f32_16x16x32_f16 v[118:121], v[136:139], v[156:159], v[118:121]
	v_mfma_f32_16x16x32_f16 v[114:117], v[148:151], v[156:159], v[114:117]
	v_mfma_f32_16x16x32_f16 v[102:105], v[136:139], v[164:167], v[102:105]
	v_mfma_f32_16x16x32_f16 v[98:101], v[148:151], v[164:167], v[98:101]
	v_mfma_f32_16x16x32_f16 v[86:89], v[136:139], v[172:175], v[86:89]
	v_mfma_f32_16x16x32_f16 v[82:85], v[148:151], v[172:175], v[82:85]
	v_mfma_f32_16x16x32_f16 v[66:69], v[136:139], v[180:183], v[66:69]
	v_mfma_f32_16x16x32_f16 v[54:57], v[148:151], v[180:183], v[54:57]
	v_mfma_f32_16x16x32_f16 v[118:121], v[144:147], v[160:163], v[118:121]
	v_mfma_f32_16x16x32_f16 v[114:117], v[152:155], v[160:163], v[114:117]
	v_mfma_f32_16x16x32_f16 v[102:105], v[144:147], v[168:171], v[102:105]
	v_mfma_f32_16x16x32_f16 v[98:101], v[152:155], v[168:171], v[98:101]
	v_mfma_f32_16x16x32_f16 v[86:89], v[144:147], v[176:179], v[86:89]
	v_mfma_f32_16x16x32_f16 v[82:85], v[152:155], v[176:179], v[82:85]
	v_mfma_f32_16x16x32_f16 v[66:69], v[144:147], v[184:187], v[66:69]
	v_mfma_f32_16x16x32_f16 v[54:57], v[152:155], v[184:187], v[54:57]
	s_barrier
	s_mov_b32 m0, s64
	ds_read_b128 v[188:191], v254 offset:49152
	ds_read_b128 v[192:195], v254 offset:50176
	ds_read_b128 v[196:199], v254 offset:51200
	ds_read_b128 v[200:203], v254 offset:52224
	s_add_u32 s98, s86, s24
	s_addc_u32 s99, s87, s25
	global_load_lds_dwordx4 v132, s[98:99]
	s_mov_b32 m0, s65
	s_add_u32 s98, s86, s26
	s_addc_u32 s99, s87, s27
	global_load_lds_dwordx4 v132, s[98:99]
	s_barrier
	s_waitcnt lgkmcnt(0)
	v_mfma_f32_16x16x32_f16 v[122:125], v[188:191], v[156:159], v[122:125]
	v_mfma_f32_16x16x32_f16 v[126:129], v[196:199], v[156:159], v[126:129]
	v_mfma_f32_16x16x32_f16 v[106:109], v[188:191], v[164:167], v[106:109]
	v_mfma_f32_16x16x32_f16 v[110:113], v[196:199], v[164:167], v[110:113]
	v_mfma_f32_16x16x32_f16 v[90:93], v[188:191], v[172:175], v[90:93]
	v_mfma_f32_16x16x32_f16 v[94:97], v[196:199], v[172:175], v[94:97]
	v_mfma_f32_16x16x32_f16 v[74:77], v[188:191], v[180:183], v[74:77]
	v_mfma_f32_16x16x32_f16 v[78:81], v[196:199], v[180:183], v[78:81]
	v_mfma_f32_16x16x32_f16 v[122:125], v[192:195], v[160:163], v[122:125]
	v_mfma_f32_16x16x32_f16 v[126:129], v[200:203], v[160:163], v[126:129]
	v_mfma_f32_16x16x32_f16 v[106:109], v[192:195], v[168:171], v[106:109]
	v_mfma_f32_16x16x32_f16 v[110:113], v[200:203], v[168:171], v[110:113]
	v_mfma_f32_16x16x32_f16 v[90:93], v[192:195], v[176:179], v[90:93]
	v_mfma_f32_16x16x32_f16 v[94:97], v[200:203], v[176:179], v[94:97]
	v_mfma_f32_16x16x32_f16 v[74:77], v[192:195], v[184:187], v[74:77]
	v_mfma_f32_16x16x32_f16 v[78:81], v[200:203], v[184:187], v[78:81]
	s_barrier
	s_mov_b32 m0, s72
	ds_read_b128 v[156:159], v141 offset:49152
	ds_read_b128 v[160:163], v141 offset:50176
	ds_read_b128 v[164:167], v141 offset:51200
	ds_read_b128 v[168:171], v141 offset:52224
	ds_read_b128 v[172:175], v141 offset:53248
	ds_read_b128 v[176:179], v141 offset:54272
	ds_read_b128 v[180:183], v141 offset:55296
	ds_read_b128 v[184:187], v141 offset:56320
	s_add_u32 s98, s46, s24
	s_addc_u32 s99, s47, s25
	global_load_lds_dwordx4 v130, s[98:99]
	s_mov_b32 m0, s73
	s_add_u32 s98, s46, s28
	s_addc_u32 s99, s47, s29
	global_load_lds_dwordx4 v130, s[98:99]
	s_barrier
	s_waitcnt lgkmcnt(0)
	v_mfma_f32_16x16x32_f16 v[58:61], v[136:139], v[156:159], v[58:61]
	v_mfma_f32_16x16x32_f16 v[50:53], v[148:151], v[156:159], v[50:53]
	v_mfma_f32_16x16x32_f16 v[38:41], v[136:139], v[164:167], v[38:41]
	v_mfma_f32_16x16x32_f16 v[34:37], v[148:151], v[164:167], v[34:37]
	v_mfma_f32_16x16x32_f16 v[22:25], v[136:139], v[172:175], v[22:25]
	v_mfma_f32_16x16x32_f16 v[18:21], v[148:151], v[172:175], v[18:21]
	v_mfma_f32_16x16x32_f16 v[10:13], v[136:139], v[180:183], v[10:13]
	v_mfma_f32_16x16x32_f16 v[6:9], v[148:151], v[180:183], v[6:9]
	v_mfma_f32_16x16x32_f16 v[58:61], v[144:147], v[160:163], v[58:61]
	v_mfma_f32_16x16x32_f16 v[50:53], v[152:155], v[160:163], v[50:53]
	v_mfma_f32_16x16x32_f16 v[38:41], v[144:147], v[168:171], v[38:41]
	v_mfma_f32_16x16x32_f16 v[34:37], v[152:155], v[168:171], v[34:37]
	v_mfma_f32_16x16x32_f16 v[22:25], v[144:147], v[176:179], v[22:25]
	v_mfma_f32_16x16x32_f16 v[18:21], v[152:155], v[176:179], v[18:21]
	v_mfma_f32_16x16x32_f16 v[10:13], v[144:147], v[184:187], v[10:13]
	v_mfma_f32_16x16x32_f16 v[6:9], v[152:155], v[184:187], v[6:9]
	s_barrier
	s_mov_b32 m0, s74
	s_add_u32 s98, s86, s30
	s_addc_u32 s99, s87, s31
	global_load_lds_dwordx4 v132, s[98:99]
	s_mov_b32 m0, s75
	s_add_u32 s98, s86, s28
	s_addc_u32 s99, s87, s29
	global_load_lds_dwordx4 v132, s[98:99]
	s_waitcnt vmcnt(6)
	s_barrier
	v_mfma_f32_16x16x32_f16 v[62:65], v[188:191], v[156:159], v[62:65]
	v_mfma_f32_16x16x32_f16 v[70:73], v[196:199], v[156:159], v[70:73]
	v_mfma_f32_16x16x32_f16 v[42:45], v[188:191], v[164:167], v[42:45]
	v_mfma_f32_16x16x32_f16 v[46:49], v[196:199], v[164:167], v[46:49]
	v_mfma_f32_16x16x32_f16 v[26:29], v[188:191], v[172:175], v[26:29]
	v_mfma_f32_16x16x32_f16 v[30:33], v[196:199], v[172:175], v[30:33]
	v_mfma_f32_16x16x32_f16 v[14:17], v[188:191], v[180:183], v[14:17]
	v_mfma_f32_16x16x32_f16 v[2:5], v[196:199], v[180:183], v[2:5]
	v_mfma_f32_16x16x32_f16 v[62:65], v[192:195], v[160:163], v[62:65]
	v_mfma_f32_16x16x32_f16 v[70:73], v[200:203], v[160:163], v[70:73]
	v_mfma_f32_16x16x32_f16 v[42:45], v[192:195], v[168:171], v[42:45]
	v_mfma_f32_16x16x32_f16 v[46:49], v[200:203], v[168:171], v[46:49]
	v_mfma_f32_16x16x32_f16 v[26:29], v[192:195], v[176:179], v[26:29]
	v_mfma_f32_16x16x32_f16 v[30:33], v[200:203], v[176:179], v[30:33]
	v_mfma_f32_16x16x32_f16 v[14:17], v[192:195], v[184:187], v[14:17]
	v_mfma_f32_16x16x32_f16 v[2:5], v[200:203], v[184:187], v[2:5]
	s_add_i32 s85, s85, 2
	s_cmp_gt_u32 s85, 29
	s_barrier
	s_cbranch_scc1 .LBB0_846
	s_cmp_eq_u32 s85, 28
	s_cbranch_scc1 .LBB0_844
	s_add_u32 s46, s44, 0xffe80080
	s_addc_u32 s47, s45, -1
	s_mov_b32 s87, s84
	s_mov_b32 s86, s51
	s_branch .Lg2_body2
